# ssq butterfly reductions and SSD per-chunk cumsum via DPP instead of ds_bpermute round trips
# speedup vs baseline: 1.1009x; 1.0076x over previous
.LBB0_704:
	s_or_b64 exec, exec, s[48:49]
	v_mul_f32_e32 v1, v112, v112
	v_fmac_f32_e32 v1, v108, v108
	v_fmac_f32_e32 v1, v116, v116
	v_fmac_f32_e32 v1, v120, v120
	s_and_b64 s[48:49], s[2:3], s[44:45]
	s_waitcnt lgkmcnt(0)
	s_nop 1
	v_add_f32_dpp v1, v1, v1 quad_perm:[1,0,3,2] row_mask:0xf bank_mask:0xf
	s_waitcnt lgkmcnt(0)
	s_nop 1
	v_add_f32_dpp v1, v1, v1 quad_perm:[2,3,0,1] row_mask:0xf bank_mask:0xf
	s_waitcnt lgkmcnt(0)
	s_nop 1
	v_add_f32_dpp v1, v1, v1 row_half_mirror row_mask:0xf bank_mask:0xf
	s_nop 1
	v_add_f32_dpp v1, v1, v1 row_mirror row_mask:0xf bank_mask:0xf
	s_and_saveexec_b64 s[44:45], s[48:49]
	s_cbranch_execz .LBB0_706
	v_lshlrev_b64 v[182:183], 6, v[182:183]
	s_waitcnt lgkmcnt(0)
	v_lshl_add_u64 v[182:183], s[46:47], 0, v[182:183]
	global_store_dword v[182:183], v1, off
.LBB0_706:
	s_or_b64 exec, exec, s[44:45]
	v_mul_f32_e32 v1, v113, v113
	v_fmac_f32_e32 v1, v109, v109
	v_fmac_f32_e32 v1, v117, v117
	v_fmac_f32_e32 v1, v121, v121
	s_waitcnt lgkmcnt(0)
	s_and_b64 s[44:45], s[2:3], s[42:43]
	s_waitcnt lgkmcnt(0)
	s_nop 1
	v_add_f32_dpp v1, v1, v1 quad_perm:[1,0,3,2] row_mask:0xf bank_mask:0xf
	s_waitcnt lgkmcnt(0)
	s_nop 1
	v_add_f32_dpp v1, v1, v1 quad_perm:[2,3,0,1] row_mask:0xf bank_mask:0xf
	s_waitcnt lgkmcnt(0)
	s_nop 1
	v_add_f32_dpp v1, v1, v1 row_half_mirror row_mask:0xf bank_mask:0xf
	s_nop 1
	v_add_f32_dpp v1, v1, v1 row_mirror row_mask:0xf bank_mask:0xf
	s_and_saveexec_b64 s[42:43], s[44:45]
	s_cbranch_execz .LBB0_708
	s_waitcnt lgkmcnt(0)
	v_lshlrev_b64 v[108:109], 6, v[180:181]
	v_lshl_add_u64 v[108:109], s[46:47], 0, v[108:109]
	global_store_dword v[108:109], v1, off
.LBB0_708:
	s_or_b64 exec, exec, s[42:43]
	v_mul_f32_e32 v1, v114, v114
	v_fmac_f32_e32 v1, v110, v110
	v_fmac_f32_e32 v1, v118, v118
	v_fmac_f32_e32 v1, v122, v122
	s_waitcnt lgkmcnt(0)
	s_and_b64 s[42:43], s[2:3], s[40:41]
	s_waitcnt lgkmcnt(0)
	s_nop 1
	v_add_f32_dpp v1, v1, v1 quad_perm:[1,0,3,2] row_mask:0xf bank_mask:0xf
	s_waitcnt lgkmcnt(0)
	s_nop 1
	v_add_f32_dpp v1, v1, v1 quad_perm:[2,3,0,1] row_mask:0xf bank_mask:0xf
	s_waitcnt lgkmcnt(0)
	s_nop 1
	v_add_f32_dpp v1, v1, v1 row_half_mirror row_mask:0xf bank_mask:0xf
	s_nop 1
	v_add_f32_dpp v1, v1, v1 row_mirror row_mask:0xf bank_mask:0xf
	s_and_saveexec_b64 s[40:41], s[42:43]
	s_cbranch_execz .LBB0_710
	s_waitcnt lgkmcnt(0)
	v_lshlrev_b64 v[108:109], 6, v[178:179]
	v_lshl_add_u64 v[108:109], s[46:47], 0, v[108:109]
	global_store_dword v[108:109], v1, off
.LBB0_710:
	s_or_b64 exec, exec, s[40:41]
	v_mul_f32_e32 v1, v115, v115
	v_fmac_f32_e32 v1, v111, v111
	v_fmac_f32_e32 v1, v119, v119
	v_fmac_f32_e32 v1, v123, v123
	s_waitcnt lgkmcnt(0)
	s_and_b64 s[42:43], s[2:3], vcc
	s_waitcnt lgkmcnt(0)
	s_nop 1
	v_add_f32_dpp v1, v1, v1 quad_perm:[1,0,3,2] row_mask:0xf bank_mask:0xf
	s_waitcnt lgkmcnt(0)
	s_nop 1
	v_add_f32_dpp v1, v1, v1 quad_perm:[2,3,0,1] row_mask:0xf bank_mask:0xf
	s_waitcnt lgkmcnt(0)
	s_nop 1
	v_add_f32_dpp v1, v1, v1 row_half_mirror row_mask:0xf bank_mask:0xf
	s_nop 1
	v_add_f32_dpp v1, v1, v1 row_mirror row_mask:0xf bank_mask:0xf
	s_and_saveexec_b64 s[40:41], s[42:43]
	s_cbranch_execz .LBB0_661
	v_lshlrev_b64 v[2:3], 6, v[2:3]
	s_waitcnt lgkmcnt(0)
	v_lshl_add_u64 v[2:3], s[46:47], 0, v[2:3]
	global_store_dword v[2:3], v1, off
	s_branch .LBB0_661

.LBB0_1518:
	s_or_b64 exec, exec, s[34:35]
	v_and_b32_e32 v3, 64, v122
	v_add_u32_e32 v97, -1, v122
	v_cmp_lt_i32_e64 s[20:21], v97, v3
	s_waitcnt vmcnt(0)
	v_mul_f32_e64 v1, v2, -v129
	v_cndmask_b32_e64 v97, v97, v122, s[20:21]
	v_lshlrev_b32_e32 v97, 2, v97
	s_nop 1
	v_add_f32_dpp v1, v1, v1 row_shr:1 row_mask:0xf bank_mask:0xf
	v_add_u32_e32 v97, -2, v122
	v_cmp_lt_i32_e64 s[20:21], v97, v3
	s_nop 1
	v_cndmask_b32_e64 v97, v97, v122, s[20:21]
	v_lshlrev_b32_e32 v97, 2, v97
	s_nop 1
	v_add_f32_dpp v1, v1, v1 row_shr:2 row_mask:0xf bank_mask:0xf
	v_add_u32_e32 v97, -4, v122
	v_cmp_lt_i32_e64 s[20:21], v97, v3
	s_nop 1
	v_cndmask_b32_e64 v97, v97, v122, s[20:21]
	v_lshlrev_b32_e32 v97, 2, v97
	s_nop 1
	v_add_f32_dpp v1, v1, v1 row_shr:4 row_mask:0xf bank_mask:0xf
	v_add_u32_e32 v97, -8, v122
	v_cmp_lt_i32_e64 s[20:21], v97, v3
	s_nop 1
	v_cndmask_b32_e64 v97, v97, v122, s[20:21]
	v_lshlrev_b32_e32 v97, 2, v97
	s_nop 1
	v_add_f32_dpp v1, v1, v1 row_shr:8 row_mask:0xf bank_mask:0xf
	v_add_u32_e32 v97, -16, v122
	v_cmp_lt_i32_e64 s[20:21], v97, v3
	s_nop 1
	v_cndmask_b32_e64 v97, v97, v122, s[20:21]
	v_lshlrev_b32_e32 v97, 2, v97
	s_nop 1
	v_add_f32_dpp v1, v1, v1 row_bcast:15 row_mask:0xa bank_mask:0xf
	v_subrev_u32_e32 v97, 32, v122
	v_cmp_lt_i32_e64 s[20:21], v97, v3
	s_nop 1
	v_cndmask_b32_e64 v3, v97, v122, s[20:21]
	v_lshlrev_b32_e32 v3, 2, v3
	s_nop 1
	v_add_f32_dpp v1, v1, v1 row_bcast:31 row_mask:0xc bank_mask:0xf
	ds_write_b32 v75, v1
	ds_write_b32 v112, v2

.LBB0_1533:
	s_barrier
	s_and_saveexec_b64 s[22:23], vcc
	s_cbranch_execz .LBB0_1535
	s_waitcnt vmcnt(0)
	v_add_f32_e32 v1, v130, v1
	v_mul_f32_e64 v2, |v1|, s33
	v_exp_f32_e32 v97, v2
	v_max_f32_e32 v1, 0, v1
	v_add_f32_e32 v98, 1.0, v97
	v_cvt_f64_f32_e32 v[2:3], v98
	v_frexp_mant_f32_e32 v99, v98
	v_frexp_exp_i32_f64_e32 v2, v[2:3]
	v_cmp_gt_f32_e64 s[20:21], s36, v99
	v_add_f32_e32 v103, -1.0, v98
	v_sub_f32_e32 v104, v97, v103
	v_subbrev_co_u32_e64 v2, s[20:21], 0, v2, s[20:21]
	v_cvt_f32_i32_e32 v3, v2
	v_sub_u32_e32 v2, 0, v2
	v_ldexp_f32 v99, v98, v2
	v_sub_f32_e32 v98, v103, v98
	v_add_f32_e32 v98, 1.0, v98
	v_add_f32_e32 v103, 1.0, v99
	v_add_f32_e32 v98, v104, v98
	v_add_f32_e32 v104, -1.0, v103
	v_ldexp_f32 v2, v98, v2
	v_sub_f32_e32 v104, v99, v104
	v_add_f32_e32 v104, v2, v104
	v_add_f32_e32 v102, -1.0, v99
	v_add_f32_e32 v105, v103, v104
	v_add_f32_e32 v98, 1.0, v102
	v_rcp_f32_e32 v106, v105
	v_sub_f32_e32 v98, v99, v98
	v_add_f32_e32 v2, v2, v98
	v_add_f32_e32 v98, v102, v2
	v_mul_f32_e32 v99, v98, v106
	v_mul_f32_e32 v107, v105, v99
	v_sub_f32_e32 v103, v105, v103
	v_sub_f32_e32 v103, v104, v103
	v_fma_f32 v104, v99, v105, -v107
	v_fmac_f32_e32 v104, v99, v103
	v_add_f32_e32 v108, v107, v104
	v_sub_f32_e32 v109, v98, v108
	v_sub_f32_e32 v102, v98, v102
	v_sub_f32_e32 v98, v98, v109
	v_sub_f32_e32 v107, v108, v107
	v_sub_f32_e32 v2, v2, v102
	v_sub_f32_e32 v98, v98, v108
	v_sub_f32_e32 v104, v107, v104
	v_add_f32_e32 v2, v2, v98
	v_add_f32_e32 v2, v104, v2
	v_add_f32_e32 v98, v109, v2
	v_mul_f32_e32 v102, v106, v98
	v_mul_f32_e32 v107, v105, v102
	v_add_f32_e32 v104, v99, v102
	v_fma_f32 v105, v102, v105, -v107
	v_sub_f32_e32 v99, v104, v99
	v_fmac_f32_e32 v105, v102, v103
	v_sub_f32_e32 v99, v102, v99
	v_add_f32_e32 v102, v107, v105
	v_sub_f32_e32 v103, v98, v102
	v_sub_f32_e32 v107, v102, v107
	v_sub_f32_e32 v105, v107, v105
	v_sub_f32_e32 v107, v109, v98
	v_sub_f32_e32 v98, v98, v103
	v_add_f32_e32 v2, v2, v107
	v_sub_f32_e32 v98, v98, v102
	v_add_f32_e32 v2, v2, v98
	v_add_f32_e32 v2, v105, v2
	v_add_f32_e32 v2, v103, v2
	v_mul_f32_e32 v2, v106, v2
	v_add_f32_e32 v2, v99, v2
	v_add_f32_e32 v98, v104, v2
	v_mul_f32_e32 v102, v98, v98
	v_fmamk_f32 v105, v102, 0x3e9b6dac, v117
	v_mul_f32_e32 v103, v98, v102
	v_fmaak_f32 v102, v102, v105, 0x3f2aaada
	v_ldexp_f32 v99, v98, 1
	v_mul_f32_e32 v102, v103, v102
	v_add_f32_e32 v103, v99, v102
	v_sub_f32_e32 v98, v98, v104
	v_mul_f32_e32 v100, 0x3f317218, v3
	v_sub_f32_e32 v2, v2, v98
	v_sub_f32_e32 v98, v103, v99
	v_fma_f32 v101, v3, s37, -v100
	v_ldexp_f32 v2, v2, 1
	v_sub_f32_e32 v98, v102, v98
	v_fmac_f32_e32 v101, 0xb102e308, v3
	v_add_f32_e32 v2, v2, v98
	v_add_f32_e32 v3, v100, v101
	v_add_f32_e32 v98, v103, v2
	v_add_f32_e32 v99, v3, v98
	v_sub_f32_e32 v100, v3, v100
	v_sub_f32_e32 v102, v99, v3
	v_sub_f32_e32 v100, v101, v100
	v_sub_f32_e32 v101, v98, v103
	v_sub_f32_e32 v98, v98, v102
	v_sub_f32_e32 v102, v99, v102
	v_sub_f32_e32 v2, v2, v101
	v_sub_f32_e32 v3, v3, v102
	v_add_f32_e32 v101, v100, v2
	v_add_f32_e32 v3, v98, v3
	v_add_f32_e32 v3, v101, v3
	v_sub_f32_e32 v102, v101, v100
	v_add_f32_e32 v98, v99, v3
	v_sub_f32_e32 v101, v101, v102
	v_sub_f32_e32 v2, v2, v102
	v_sub_f32_e32 v100, v100, v101
	v_sub_f32_e32 v99, v98, v99
	v_add_f32_e32 v2, v2, v100
	v_sub_f32_e32 v3, v3, v99
	v_add_f32_e32 v2, v2, v3
	v_add_f32_e32 v2, v98, v2
	v_cmp_neq_f32_e64 s[20:21], s38, v97
	v_and_b32_e32 v3, 64, v122
	s_nop 0
	v_cndmask_b32_e64 v2, v119, v2, s[20:21]
	v_cmp_ngt_f32_e64 s[20:21], -1.0, v97
	s_nop 1
	v_cndmask_b32_e64 v2, v120, v2, s[20:21]
	v_cmp_neq_f32_e64 s[20:21], -1.0, v97
	s_nop 1
	v_cndmask_b32_e64 v2, v121, v2, s[20:21]
	v_cmp_lt_f32_e64 s[20:21], |v97|, s39
	s_nop 1
	v_cndmask_b32_e64 v2, v2, v97, s[20:21]
	v_add_u32_e32 v97, -1, v122
	v_cmp_lt_i32_e64 s[20:21], v97, v3
	v_add_f32_e32 v1, v1, v2
	v_mul_f32_e64 v2, v1, -v129
	v_cndmask_b32_e64 v97, v97, v122, s[20:21]
	v_lshlrev_b32_e32 v97, 2, v97
	s_nop 1
	v_add_f32_dpp v2, v2, v2 row_shr:1 row_mask:0xf bank_mask:0xf
	v_add_u32_e32 v97, -2, v122
	v_cmp_lt_i32_e64 s[20:21], v97, v3
	s_nop 1
	v_cndmask_b32_e64 v97, v97, v122, s[20:21]
	v_lshlrev_b32_e32 v97, 2, v97
	s_nop 1
	v_add_f32_dpp v2, v2, v2 row_shr:2 row_mask:0xf bank_mask:0xf
	v_add_u32_e32 v97, -4, v122
	v_cmp_lt_i32_e64 s[20:21], v97, v3
	s_nop 1
	v_cndmask_b32_e64 v97, v97, v122, s[20:21]
	v_lshlrev_b32_e32 v97, 2, v97
	s_nop 1
	v_add_f32_dpp v2, v2, v2 row_shr:4 row_mask:0xf bank_mask:0xf
	v_add_u32_e32 v97, -8, v122
	v_cmp_lt_i32_e64 s[20:21], v97, v3
	s_nop 1
	v_cndmask_b32_e64 v97, v97, v122, s[20:21]
	v_lshlrev_b32_e32 v97, 2, v97
	s_nop 1
	v_add_f32_dpp v2, v2, v2 row_shr:8 row_mask:0xf bank_mask:0xf
	v_add_u32_e32 v97, -16, v122
	v_cmp_lt_i32_e64 s[20:21], v97, v3
	s_nop 1
	v_cndmask_b32_e64 v97, v97, v122, s[20:21]
	v_lshlrev_b32_e32 v97, 2, v97
	s_nop 1
	v_add_f32_dpp v2, v2, v2 row_bcast:15 row_mask:0xa bank_mask:0xf
	v_subrev_u32_e32 v97, 32, v122
	v_cmp_lt_i32_e64 s[20:21], v97, v3
	s_nop 1
	v_cndmask_b32_e64 v3, v97, v122, s[20:21]
	v_lshlrev_b32_e32 v3, 2, v3
	s_nop 1
	v_add_f32_dpp v2, v2, v2 row_bcast:31 row_mask:0xc bank_mask:0xf
	ds_write_b32 v75, v2
	ds_write_b32 v112, v1

.LBB0_1683:
	s_or_b64 exec, exec, s[58:59]
	v_mul_f32_e64 v3, v2, -v227
	s_nop 1
	v_add_f32_dpp v3, v3, v3 row_shr:1 row_mask:0xf bank_mask:0xf
	s_nop 1
	v_add_f32_dpp v3, v3, v3 row_shr:2 row_mask:0xf bank_mask:0xf
	s_nop 1
	v_add_f32_dpp v3, v3, v3 row_shr:4 row_mask:0xf bank_mask:0xf
	s_nop 1
	v_add_f32_dpp v3, v3, v3 row_shr:8 row_mask:0xf bank_mask:0xf
	s_nop 1
	v_add_f32_dpp v3, v3, v3 row_bcast:15 row_mask:0xa bank_mask:0xf
	s_nop 1
	v_add_f32_dpp v3, v3, v3 row_bcast:31 row_mask:0xc bank_mask:0xf
	ds_write_b32 v111, v3
	ds_write_b32 v151, v2

.LBB0_1760:
	s_or_b64 exec, exec, s[76:77]
	s_and_b64 s[2:3], s[6:7], vcc
	s_waitcnt lgkmcnt(0)
	s_nop 1
	v_add_f32_dpp v60, v229, v229 quad_perm:[1,0,3,2] row_mask:0xf bank_mask:0xf
	s_waitcnt lgkmcnt(0)
	s_nop 1
	v_add_f32_dpp v60, v60, v60 quad_perm:[2,3,0,1] row_mask:0xf bank_mask:0xf
	s_waitcnt lgkmcnt(0)
	s_nop 1
	v_add_f32_dpp v60, v60, v60 row_half_mirror row_mask:0xf bank_mask:0xf
	s_nop 1
	v_add_f32_dpp v60, v60, v60 row_mirror row_mask:0xf bank_mask:0xf
	s_and_saveexec_b64 s[76:77], s[2:3]
	s_cbranch_execz .LBB0_1762
	v_lshlrev_b64 v[2:3], 7, v[2:3]
	v_lshl_add_u64 v[2:3], s[92:93], 0, v[2:3]
	s_waitcnt lgkmcnt(0)
	global_store_dword v[2:3], v60, off
.LBB0_1762:
	s_or_b64 exec, exec, s[76:77]
	s_and_b64 s[2:3], s[6:7], s[54:55]
	s_waitcnt lgkmcnt(0)
	s_nop 1
	v_add_f32_dpp v2, v230, v230 quad_perm:[1,0,3,2] row_mask:0xf bank_mask:0xf
	s_waitcnt lgkmcnt(0)
	s_nop 1
	v_add_f32_dpp v2, v2, v2 quad_perm:[2,3,0,1] row_mask:0xf bank_mask:0xf
	s_waitcnt lgkmcnt(0)
	s_nop 1
	v_add_f32_dpp v2, v2, v2 row_half_mirror row_mask:0xf bank_mask:0xf
	s_nop 1
	v_add_f32_dpp v2, v2, v2 row_mirror row_mask:0xf bank_mask:0xf
	s_and_saveexec_b64 s[54:55], s[2:3]
	s_cbranch_execz .LBB0_1764
	v_lshlrev_b64 v[60:61], 7, v[92:93]
	v_lshl_add_u64 v[60:61], s[92:93], 0, v[60:61]
	s_waitcnt lgkmcnt(0)
	global_store_dword v[60:61], v2, off
.LBB0_1764:
	s_or_b64 exec, exec, s[54:55]
	s_and_b64 s[2:3], s[6:7], s[56:57]
	s_waitcnt lgkmcnt(0)
	s_nop 1
	v_add_f32_dpp v2, v228, v228 quad_perm:[1,0,3,2] row_mask:0xf bank_mask:0xf
	s_waitcnt lgkmcnt(0)
	s_nop 1
	v_add_f32_dpp v2, v2, v2 quad_perm:[2,3,0,1] row_mask:0xf bank_mask:0xf
	s_waitcnt lgkmcnt(0)
	s_nop 1
	v_add_f32_dpp v2, v2, v2 row_half_mirror row_mask:0xf bank_mask:0xf
	s_nop 1
	v_add_f32_dpp v2, v2, v2 row_mirror row_mask:0xf bank_mask:0xf
	s_and_saveexec_b64 s[54:55], s[2:3]
	s_cbranch_execz .LBB0_1766
	v_lshlrev_b64 v[60:61], 7, v[80:81]
	v_lshl_add_u64 v[60:61], s[92:93], 0, v[60:61]
	s_waitcnt lgkmcnt(0)
	global_store_dword v[60:61], v2, off
.LBB0_1766:
	s_or_b64 exec, exec, s[54:55]
	s_and_b64 s[2:3], s[6:7], s[58:59]
	s_waitcnt lgkmcnt(0)
	s_nop 1
	v_add_f32_dpp v2, v90, v90 quad_perm:[1,0,3,2] row_mask:0xf bank_mask:0xf
	s_waitcnt lgkmcnt(0)
	s_nop 1
	v_add_f32_dpp v2, v2, v2 quad_perm:[2,3,0,1] row_mask:0xf bank_mask:0xf
	s_waitcnt lgkmcnt(0)
	s_nop 1
	v_add_f32_dpp v2, v2, v2 row_half_mirror row_mask:0xf bank_mask:0xf
	s_nop 1
	v_add_f32_dpp v2, v2, v2 row_mirror row_mask:0xf bank_mask:0xf
	s_and_saveexec_b64 s[54:55], s[2:3]
	s_cbranch_execz .LBB0_1679
	v_lshlrev_b64 v[60:61], 7, v[88:89]
	v_lshl_add_u64 v[60:61], s[92:93], 0, v[60:61]
	s_waitcnt lgkmcnt(0)
	global_store_dword v[60:61], v2, off
	s_branch .LBB0_1679

.LBB0_2444:
	s_or_b64 exec, exec, s[52:53]
	v_mul_f32_e32 v1, v120, v120
	v_fmac_f32_e32 v1, v108, v108
	v_fmac_f32_e32 v1, v116, v116
	v_fmac_f32_e32 v1, v112, v112
	s_and_b64 s[52:53], s[4:5], s[46:47]
	s_waitcnt lgkmcnt(0)
	s_nop 1
	v_add_f32_dpp v1, v1, v1 quad_perm:[1,0,3,2] row_mask:0xf bank_mask:0xf
	s_waitcnt lgkmcnt(0)
	s_nop 1
	v_add_f32_dpp v1, v1, v1 quad_perm:[2,3,0,1] row_mask:0xf bank_mask:0xf
	s_waitcnt lgkmcnt(0)
	s_nop 1
	v_add_f32_dpp v1, v1, v1 row_half_mirror row_mask:0xf bank_mask:0xf
	s_nop 1
	v_add_f32_dpp v1, v1, v1 row_mirror row_mask:0xf bank_mask:0xf
	s_and_saveexec_b64 s[46:47], s[52:53]
	s_cbranch_execz .LBB0_2446
	v_lshlrev_b64 v[182:183], 6, v[182:183]
	s_waitcnt lgkmcnt(0)
	v_lshl_add_u64 v[182:183], s[50:51], 0, v[182:183]
	global_store_dword v[182:183], v1, off
.LBB0_2446:
	s_or_b64 exec, exec, s[46:47]
	v_mul_f32_e32 v1, v121, v121
	v_fmac_f32_e32 v1, v109, v109
	v_fmac_f32_e32 v1, v117, v117
	v_fmac_f32_e32 v1, v113, v113
	s_waitcnt lgkmcnt(0)
	s_and_b64 s[46:47], s[4:5], s[44:45]
	s_waitcnt lgkmcnt(0)
	s_nop 1
	v_add_f32_dpp v1, v1, v1 quad_perm:[1,0,3,2] row_mask:0xf bank_mask:0xf
	s_waitcnt lgkmcnt(0)
	s_nop 1
	v_add_f32_dpp v1, v1, v1 quad_perm:[2,3,0,1] row_mask:0xf bank_mask:0xf
	s_waitcnt lgkmcnt(0)
	s_nop 1
	v_add_f32_dpp v1, v1, v1 row_half_mirror row_mask:0xf bank_mask:0xf
	s_nop 1
	v_add_f32_dpp v1, v1, v1 row_mirror row_mask:0xf bank_mask:0xf
	s_and_saveexec_b64 s[44:45], s[46:47]
	s_cbranch_execz .LBB0_2448
	s_waitcnt lgkmcnt(0)
	v_lshlrev_b64 v[108:109], 6, v[180:181]
	v_lshl_add_u64 v[108:109], s[50:51], 0, v[108:109]
	global_store_dword v[108:109], v1, off
.LBB0_2448:
	s_or_b64 exec, exec, s[44:45]
	v_mul_f32_e32 v1, v122, v122
	v_fmac_f32_e32 v1, v110, v110
	v_fmac_f32_e32 v1, v118, v118
	v_fmac_f32_e32 v1, v114, v114
	s_waitcnt lgkmcnt(0)
	s_and_b64 s[44:45], s[4:5], s[42:43]
	s_waitcnt lgkmcnt(0)
	s_nop 1
	v_add_f32_dpp v1, v1, v1 quad_perm:[1,0,3,2] row_mask:0xf bank_mask:0xf
	s_waitcnt lgkmcnt(0)
	s_nop 1
	v_add_f32_dpp v1, v1, v1 quad_perm:[2,3,0,1] row_mask:0xf bank_mask:0xf
	s_waitcnt lgkmcnt(0)
	s_nop 1
	v_add_f32_dpp v1, v1, v1 row_half_mirror row_mask:0xf bank_mask:0xf
	s_nop 1
	v_add_f32_dpp v1, v1, v1 row_mirror row_mask:0xf bank_mask:0xf
	s_and_saveexec_b64 s[42:43], s[44:45]
	s_cbranch_execz .LBB0_2450
	s_waitcnt lgkmcnt(0)
	v_lshlrev_b64 v[108:109], 6, v[178:179]
	v_lshl_add_u64 v[108:109], s[50:51], 0, v[108:109]
	global_store_dword v[108:109], v1, off
.LBB0_2450:
	s_or_b64 exec, exec, s[42:43]
	v_mul_f32_e32 v1, v123, v123
	v_fmac_f32_e32 v1, v111, v111
	v_fmac_f32_e32 v1, v119, v119
	v_fmac_f32_e32 v1, v115, v115
	s_waitcnt lgkmcnt(0)
	s_and_b64 s[44:45], s[4:5], vcc
	s_waitcnt lgkmcnt(0)
	s_nop 1
	v_add_f32_dpp v1, v1, v1 quad_perm:[1,0,3,2] row_mask:0xf bank_mask:0xf
	s_waitcnt lgkmcnt(0)
	s_nop 1
	v_add_f32_dpp v1, v1, v1 quad_perm:[2,3,0,1] row_mask:0xf bank_mask:0xf
	s_waitcnt lgkmcnt(0)
	s_nop 1
	v_add_f32_dpp v1, v1, v1 row_half_mirror row_mask:0xf bank_mask:0xf
	s_nop 1
	v_add_f32_dpp v1, v1, v1 row_mirror row_mask:0xf bank_mask:0xf
	s_and_saveexec_b64 s[42:43], s[44:45]
	s_cbranch_execz .LBB0_2401
	v_lshlrev_b64 v[2:3], 6, v[2:3]
	s_waitcnt lgkmcnt(0)
	v_lshl_add_u64 v[2:3], s[50:51], 0, v[2:3]
	global_store_dword v[2:3], v1, off
	s_branch .LBB0_2401
